# cvec_job: rows batched, shift vectors hoisted, DPP wave reduction
# speedup vs baseline: 1.0189x; 1.0042x over previous
.LBB0_357:
	s_lshl_b32 s0, s90, 3
	s_add_i32 s0, s0, s91
	s_cmpk_lt_i32 s0, 0x1600
	s_cbranch_scc0 .LBB0_362
	s_lshl_b32 s1, s33, 3
	v_lshlrev_b32_e32 v1, 5, v242
	v_lshlrev_b32_e32 v2, 4, v242
	v_add_u32_e32 v4, 0x6000, v1
	v_mov_b32_e32 v3, 0
	s_add_u32 s6, s88, 0x1c3000
	s_addc_u32 s7, s89, 0
	global_load_dwordx4 v[28:31], v1, s[6:7]
	global_load_dwordx4 v[32:35], v4, s[6:7]
	global_load_dwordx4 v[36:39], v1, s[6:7] offset:16
	global_load_dwordx4 v[40:43], v4, s[6:7] offset:16
	global_load_dwordx4 v[44:47], v1, s[6:7] offset:2048
	global_load_dwordx4 v[48:51], v4, s[6:7] offset:2048
	global_load_dwordx4 v[52:55], v1, s[6:7] offset:2064
	global_load_dwordx4 v[56:59], v4, s[6:7] offset:2064
.Lcv0_loop:
	s_lshl_b32 s12, s0, 11
	s_add_u32 s12, s12, 0x900000
	s_add_u32 s12, s88, s12
	s_addc_u32 s13, s89, 0
	s_lshl_b32 s3, s1, 11
	global_load_dwordx4 v[60:63], v2, s[12:13]
	global_load_dwordx4 v[64:67], v2, s[12:13] offset:1024
	s_add_u32 s12, s12, s3
	s_addc_u32 s13, s13, 0
	global_load_dwordx4 v[68:71], v2, s[12:13]
	global_load_dwordx4 v[72:75], v2, s[12:13] offset:1024
	s_add_u32 s12, s12, s3
	s_addc_u32 s13, s13, 0
	global_load_dwordx4 v[76:79], v2, s[12:13]
	global_load_dwordx4 v[80:83], v2, s[12:13] offset:1024
	s_waitcnt vmcnt(0)
	v_lshlrev_b32_e32 v92, 16, v60
	v_and_b32_e32 v93, 0xffff0000, v60
	v_lshlrev_b32_e32 v96, 16, v68
	v_and_b32_e32 v97, 0xffff0000, v68
	v_lshlrev_b32_e32 v100, 16, v76
	v_and_b32_e32 v101, 0xffff0000, v76
	v_mul_f32_e32 v94, v29, v93
	v_mul_f32_e32 v95, v33, v93
	v_mul_f32_e32 v98, v29, v97
	v_mul_f32_e32 v99, v33, v97
	v_mul_f32_e32 v102, v29, v101
	v_mul_f32_e32 v103, v33, v101
	v_fmac_f32_e32 v94, v28, v92
	v_fmac_f32_e32 v95, v32, v92
	v_fmac_f32_e32 v98, v28, v96
	v_fmac_f32_e32 v99, v32, v96
	v_fmac_f32_e32 v102, v28, v100
	v_fmac_f32_e32 v103, v32, v100
	v_add_f32_e32 v84, 0, v94
	v_add_f32_e32 v85, 0, v95
	v_add_f32_e32 v86, 0, v98
	v_add_f32_e32 v87, 0, v99
	v_add_f32_e32 v88, 0, v102
	v_add_f32_e32 v89, 0, v103
	v_lshlrev_b32_e32 v92, 16, v61
	v_and_b32_e32 v93, 0xffff0000, v61
	v_lshlrev_b32_e32 v96, 16, v69
	v_and_b32_e32 v97, 0xffff0000, v69
	v_lshlrev_b32_e32 v100, 16, v77
	v_and_b32_e32 v101, 0xffff0000, v77
	v_mul_f32_e32 v94, v31, v93
	v_mul_f32_e32 v95, v35, v93
	v_mul_f32_e32 v98, v31, v97
	v_mul_f32_e32 v99, v35, v97
	v_mul_f32_e32 v102, v31, v101
	v_mul_f32_e32 v103, v35, v101
	v_fmac_f32_e32 v94, v30, v92
	v_fmac_f32_e32 v95, v34, v92
	v_fmac_f32_e32 v98, v30, v96
	v_fmac_f32_e32 v99, v34, v96
	v_fmac_f32_e32 v102, v30, v100
	v_fmac_f32_e32 v103, v34, v100
	v_add_f32_e32 v84, v84, v94
	v_add_f32_e32 v85, v85, v95
	v_add_f32_e32 v86, v86, v98
	v_add_f32_e32 v87, v87, v99
	v_add_f32_e32 v88, v88, v102
	v_add_f32_e32 v89, v89, v103
	v_lshlrev_b32_e32 v92, 16, v62
	v_and_b32_e32 v93, 0xffff0000, v62
	v_lshlrev_b32_e32 v96, 16, v70
	v_and_b32_e32 v97, 0xffff0000, v70
	v_lshlrev_b32_e32 v100, 16, v78
	v_and_b32_e32 v101, 0xffff0000, v78
	v_mul_f32_e32 v94, v37, v93
	v_mul_f32_e32 v95, v41, v93
	v_mul_f32_e32 v98, v37, v97
	v_mul_f32_e32 v99, v41, v97
	v_mul_f32_e32 v102, v37, v101
	v_mul_f32_e32 v103, v41, v101
	v_fmac_f32_e32 v94, v36, v92
	v_fmac_f32_e32 v95, v40, v92
	v_fmac_f32_e32 v98, v36, v96
	v_fmac_f32_e32 v99, v40, v96
	v_fmac_f32_e32 v102, v36, v100
	v_fmac_f32_e32 v103, v40, v100
	v_add_f32_e32 v84, v84, v94
	v_add_f32_e32 v85, v85, v95
	v_add_f32_e32 v86, v86, v98
	v_add_f32_e32 v87, v87, v99
	v_add_f32_e32 v88, v88, v102
	v_add_f32_e32 v89, v89, v103
	v_lshlrev_b32_e32 v92, 16, v63
	v_and_b32_e32 v93, 0xffff0000, v63
	v_lshlrev_b32_e32 v96, 16, v71
	v_and_b32_e32 v97, 0xffff0000, v71
	v_lshlrev_b32_e32 v100, 16, v79
	v_and_b32_e32 v101, 0xffff0000, v79
	v_mul_f32_e32 v94, v39, v93
	v_mul_f32_e32 v95, v43, v93
	v_mul_f32_e32 v98, v39, v97
	v_mul_f32_e32 v99, v43, v97
	v_mul_f32_e32 v102, v39, v101
	v_mul_f32_e32 v103, v43, v101
	v_fmac_f32_e32 v94, v38, v92
	v_fmac_f32_e32 v95, v42, v92
	v_fmac_f32_e32 v98, v38, v96
	v_fmac_f32_e32 v99, v42, v96
	v_fmac_f32_e32 v102, v38, v100
	v_fmac_f32_e32 v103, v42, v100
	v_add_f32_e32 v84, v84, v94
	v_add_f32_e32 v85, v85, v95
	v_add_f32_e32 v86, v86, v98
	v_add_f32_e32 v87, v87, v99
	v_add_f32_e32 v88, v88, v102
	v_add_f32_e32 v89, v89, v103
	v_lshlrev_b32_e32 v92, 16, v64
	v_and_b32_e32 v93, 0xffff0000, v64
	v_lshlrev_b32_e32 v96, 16, v72
	v_and_b32_e32 v97, 0xffff0000, v72
	v_lshlrev_b32_e32 v100, 16, v80
	v_and_b32_e32 v101, 0xffff0000, v80
	v_mul_f32_e32 v94, v45, v93
	v_mul_f32_e32 v95, v49, v93
	v_mul_f32_e32 v98, v45, v97
	v_mul_f32_e32 v99, v49, v97
	v_mul_f32_e32 v102, v45, v101
	v_mul_f32_e32 v103, v49, v101
	v_fmac_f32_e32 v94, v44, v92
	v_fmac_f32_e32 v95, v48, v92
	v_fmac_f32_e32 v98, v44, v96
	v_fmac_f32_e32 v99, v48, v96
	v_fmac_f32_e32 v102, v44, v100
	v_fmac_f32_e32 v103, v48, v100
	v_add_f32_e32 v84, v84, v94
	v_add_f32_e32 v85, v85, v95
	v_add_f32_e32 v86, v86, v98
	v_add_f32_e32 v87, v87, v99
	v_add_f32_e32 v88, v88, v102
	v_add_f32_e32 v89, v89, v103
	v_lshlrev_b32_e32 v92, 16, v65
	v_and_b32_e32 v93, 0xffff0000, v65
	v_lshlrev_b32_e32 v96, 16, v73
	v_and_b32_e32 v97, 0xffff0000, v73
	v_lshlrev_b32_e32 v100, 16, v81
	v_and_b32_e32 v101, 0xffff0000, v81
	v_mul_f32_e32 v94, v47, v93
	v_mul_f32_e32 v95, v51, v93
	v_mul_f32_e32 v98, v47, v97
	v_mul_f32_e32 v99, v51, v97
	v_mul_f32_e32 v102, v47, v101
	v_mul_f32_e32 v103, v51, v101
	v_fmac_f32_e32 v94, v46, v92
	v_fmac_f32_e32 v95, v50, v92
	v_fmac_f32_e32 v98, v46, v96
	v_fmac_f32_e32 v99, v50, v96
	v_fmac_f32_e32 v102, v46, v100
	v_fmac_f32_e32 v103, v50, v100
	v_add_f32_e32 v84, v84, v94
	v_add_f32_e32 v85, v85, v95
	v_add_f32_e32 v86, v86, v98
	v_add_f32_e32 v87, v87, v99
	v_add_f32_e32 v88, v88, v102
	v_add_f32_e32 v89, v89, v103
	v_lshlrev_b32_e32 v92, 16, v66
	v_and_b32_e32 v93, 0xffff0000, v66
	v_lshlrev_b32_e32 v96, 16, v74
	v_and_b32_e32 v97, 0xffff0000, v74
	v_lshlrev_b32_e32 v100, 16, v82
	v_and_b32_e32 v101, 0xffff0000, v82
	v_mul_f32_e32 v94, v53, v93
	v_mul_f32_e32 v95, v57, v93
	v_mul_f32_e32 v98, v53, v97
	v_mul_f32_e32 v99, v57, v97
	v_mul_f32_e32 v102, v53, v101
	v_mul_f32_e32 v103, v57, v101
	v_fmac_f32_e32 v94, v52, v92
	v_fmac_f32_e32 v95, v56, v92
	v_fmac_f32_e32 v98, v52, v96
	v_fmac_f32_e32 v99, v56, v96
	v_fmac_f32_e32 v102, v52, v100
	v_fmac_f32_e32 v103, v56, v100
	v_add_f32_e32 v84, v84, v94
	v_add_f32_e32 v85, v85, v95
	v_add_f32_e32 v86, v86, v98
	v_add_f32_e32 v87, v87, v99
	v_add_f32_e32 v88, v88, v102
	v_add_f32_e32 v89, v89, v103
	v_lshlrev_b32_e32 v92, 16, v67
	v_and_b32_e32 v93, 0xffff0000, v67
	v_lshlrev_b32_e32 v96, 16, v75
	v_and_b32_e32 v97, 0xffff0000, v75
	v_lshlrev_b32_e32 v100, 16, v83
	v_and_b32_e32 v101, 0xffff0000, v83
	v_mul_f32_e32 v94, v55, v93
	v_mul_f32_e32 v95, v59, v93
	v_mul_f32_e32 v98, v55, v97
	v_mul_f32_e32 v99, v59, v97
	v_mul_f32_e32 v102, v55, v101
	v_mul_f32_e32 v103, v59, v101
	v_fmac_f32_e32 v94, v54, v92
	v_fmac_f32_e32 v95, v58, v92
	v_fmac_f32_e32 v98, v54, v96
	v_fmac_f32_e32 v99, v58, v96
	v_fmac_f32_e32 v102, v54, v100
	v_fmac_f32_e32 v103, v58, v100
	v_add_f32_e32 v84, v84, v94
	v_add_f32_e32 v85, v85, v95
	v_add_f32_e32 v86, v86, v98
	v_add_f32_e32 v87, v87, v99
	v_add_f32_e32 v88, v88, v102
	v_add_f32_e32 v89, v89, v103
	s_nop 1
	v_add_f32_dpp v84, v84, v84 quad_perm:[1,0,3,2] row_mask:0xf bank_mask:0xf
	v_add_f32_dpp v85, v85, v85 quad_perm:[1,0,3,2] row_mask:0xf bank_mask:0xf
	v_add_f32_dpp v86, v86, v86 quad_perm:[1,0,3,2] row_mask:0xf bank_mask:0xf
	v_add_f32_dpp v87, v87, v87 quad_perm:[1,0,3,2] row_mask:0xf bank_mask:0xf
	v_add_f32_dpp v88, v88, v88 quad_perm:[1,0,3,2] row_mask:0xf bank_mask:0xf
	v_add_f32_dpp v89, v89, v89 quad_perm:[1,0,3,2] row_mask:0xf bank_mask:0xf
	v_add_f32_dpp v84, v84, v84 quad_perm:[2,3,0,1] row_mask:0xf bank_mask:0xf
	v_add_f32_dpp v85, v85, v85 quad_perm:[2,3,0,1] row_mask:0xf bank_mask:0xf
	v_add_f32_dpp v86, v86, v86 quad_perm:[2,3,0,1] row_mask:0xf bank_mask:0xf
	v_add_f32_dpp v87, v87, v87 quad_perm:[2,3,0,1] row_mask:0xf bank_mask:0xf
	v_add_f32_dpp v88, v88, v88 quad_perm:[2,3,0,1] row_mask:0xf bank_mask:0xf
	v_add_f32_dpp v89, v89, v89 quad_perm:[2,3,0,1] row_mask:0xf bank_mask:0xf
	v_add_f32_dpp v84, v84, v84 row_half_mirror row_mask:0xf bank_mask:0xf
	v_add_f32_dpp v85, v85, v85 row_half_mirror row_mask:0xf bank_mask:0xf
	v_add_f32_dpp v86, v86, v86 row_half_mirror row_mask:0xf bank_mask:0xf
	v_add_f32_dpp v87, v87, v87 row_half_mirror row_mask:0xf bank_mask:0xf
	v_add_f32_dpp v88, v88, v88 row_half_mirror row_mask:0xf bank_mask:0xf
	v_add_f32_dpp v89, v89, v89 row_half_mirror row_mask:0xf bank_mask:0xf
	v_add_f32_dpp v84, v84, v84 row_mirror row_mask:0xf bank_mask:0xf
	v_add_f32_dpp v85, v85, v85 row_mirror row_mask:0xf bank_mask:0xf
	v_add_f32_dpp v86, v86, v86 row_mirror row_mask:0xf bank_mask:0xf
	v_add_f32_dpp v87, v87, v87 row_mirror row_mask:0xf bank_mask:0xf
	v_add_f32_dpp v88, v88, v88 row_mirror row_mask:0xf bank_mask:0xf
	v_add_f32_dpp v89, v89, v89 row_mirror row_mask:0xf bank_mask:0xf
	v_add_f32_dpp v84, v84, v84 row_bcast:15 row_mask:0xa bank_mask:0xf
	v_add_f32_dpp v85, v85, v85 row_bcast:15 row_mask:0xa bank_mask:0xf
	v_add_f32_dpp v86, v86, v86 row_bcast:15 row_mask:0xa bank_mask:0xf
	v_add_f32_dpp v87, v87, v87 row_bcast:15 row_mask:0xa bank_mask:0xf
	v_add_f32_dpp v88, v88, v88 row_bcast:15 row_mask:0xa bank_mask:0xf
	v_add_f32_dpp v89, v89, v89 row_bcast:15 row_mask:0xa bank_mask:0xf
	v_add_f32_dpp v84, v84, v84 row_bcast:31 row_mask:0xc bank_mask:0xf
	v_add_f32_dpp v85, v85, v85 row_bcast:31 row_mask:0xc bank_mask:0xf
	v_add_f32_dpp v86, v86, v86 row_bcast:31 row_mask:0xc bank_mask:0xf
	v_add_f32_dpp v87, v87, v87 row_bcast:31 row_mask:0xc bank_mask:0xf
	v_add_f32_dpp v88, v88, v88 row_bcast:31 row_mask:0xc bank_mask:0xf
	v_add_f32_dpp v89, v89, v89 row_bcast:31 row_mask:0xc bank_mask:0xf
	v_cmp_eq_u32_e32 vcc, 63, v242
	s_lshl_b32 s14, s0, 2
	s_add_u32 s14, s14, 0x2d0000
	s_add_u32 s14, s88, s14
	s_addc_u32 s15, s89, 0
	s_lshl_b32 s3, s1, 2
	s_and_saveexec_b64 s[4:5], vcc
	global_store_dword v3, v84, s[14:15]
	s_add_u32 s12, s14, 0x5800
	s_addc_u32 s13, s15, 0
	global_store_dword v3, v85, s[12:13]
	s_add_i32 s0, s0, s1
	s_add_u32 s14, s14, s3
	s_addc_u32 s15, s15, 0
	s_cmpk_lt_i32 s0, 0x1600
	s_cbranch_scc0 .Lcv0_skip1
	global_store_dword v3, v86, s[14:15]
	s_add_u32 s12, s14, 0x5800
	s_addc_u32 s13, s15, 0
	global_store_dword v3, v87, s[12:13]
	s_add_i32 s0, s0, s1
	s_add_u32 s14, s14, s3
	s_addc_u32 s15, s15, 0
	s_cmpk_lt_i32 s0, 0x1600
	s_cbranch_scc0 .Lcv0_skip2
	global_store_dword v3, v88, s[14:15]
	s_add_u32 s12, s14, 0x5800
	s_addc_u32 s13, s15, 0
	global_store_dword v3, v89, s[12:13]
	s_or_b64 exec, exec, s[4:5]
	s_add_i32 s0, s0, s1
	s_cmpk_lt_i32 s0, 0x1600
	s_cbranch_scc1 .Lcv0_loop
	s_branch .LBB0_362
.Lcv0_skip1:
.Lcv0_skip2:
	s_or_b64 exec, exec, s[4:5]

.LBB0_1111:
	v_readlane_b32 s0, v255, 10
	s_lshl_b32 s0, s0, 3
	s_add_i32 s0, s0, s91
	s_cmpk_lt_i32 s0, 0x1600
	s_cbranch_scc0 .LBB0_1116
	s_lshl_b32 s1, s33, 3
	v_lshlrev_b32_e32 v1, 5, v242
	v_lshlrev_b32_e32 v2, 4, v242
	v_add_u32_e32 v4, 0x6000, v1
	v_mov_b32_e32 v3, 0
	s_add_u32 s6, s88, 0x1cf000
	s_addc_u32 s7, s89, 0
	global_load_dwordx4 v[28:31], v1, s[6:7]
	global_load_dwordx4 v[32:35], v4, s[6:7]
	global_load_dwordx4 v[36:39], v1, s[6:7] offset:16
	global_load_dwordx4 v[40:43], v4, s[6:7] offset:16
	global_load_dwordx4 v[44:47], v1, s[6:7] offset:2048
	global_load_dwordx4 v[48:51], v4, s[6:7] offset:2048
	global_load_dwordx4 v[52:55], v1, s[6:7] offset:2064
	global_load_dwordx4 v[56:59], v4, s[6:7] offset:2064
.Lcv1_loop:
	s_lshl_b32 s12, s0, 11
	s_add_u32 s12, s12, 0x1400000
	s_add_u32 s12, s88, s12
	s_addc_u32 s13, s89, 0
	s_lshl_b32 s3, s1, 11
	global_load_dwordx4 v[60:63], v2, s[12:13]
	global_load_dwordx4 v[64:67], v2, s[12:13] offset:1024
	s_add_u32 s12, s12, s3
	s_addc_u32 s13, s13, 0
	global_load_dwordx4 v[68:71], v2, s[12:13]
	global_load_dwordx4 v[72:75], v2, s[12:13] offset:1024
	s_add_u32 s12, s12, s3
	s_addc_u32 s13, s13, 0
	global_load_dwordx4 v[76:79], v2, s[12:13]
	global_load_dwordx4 v[80:83], v2, s[12:13] offset:1024
	s_waitcnt vmcnt(0)
	v_lshlrev_b32_e32 v92, 16, v60
	v_and_b32_e32 v93, 0xffff0000, v60
	v_lshlrev_b32_e32 v96, 16, v68
	v_and_b32_e32 v97, 0xffff0000, v68
	v_lshlrev_b32_e32 v100, 16, v76
	v_and_b32_e32 v101, 0xffff0000, v76
	v_mul_f32_e32 v94, v29, v93
	v_mul_f32_e32 v95, v33, v93
	v_mul_f32_e32 v98, v29, v97
	v_mul_f32_e32 v99, v33, v97
	v_mul_f32_e32 v102, v29, v101
	v_mul_f32_e32 v103, v33, v101
	v_fmac_f32_e32 v94, v28, v92
	v_fmac_f32_e32 v95, v32, v92
	v_fmac_f32_e32 v98, v28, v96
	v_fmac_f32_e32 v99, v32, v96
	v_fmac_f32_e32 v102, v28, v100
	v_fmac_f32_e32 v103, v32, v100
	v_add_f32_e32 v84, 0, v94
	v_add_f32_e32 v85, 0, v95
	v_add_f32_e32 v86, 0, v98
	v_add_f32_e32 v87, 0, v99
	v_add_f32_e32 v88, 0, v102
	v_add_f32_e32 v89, 0, v103
	v_lshlrev_b32_e32 v92, 16, v61
	v_and_b32_e32 v93, 0xffff0000, v61
	v_lshlrev_b32_e32 v96, 16, v69
	v_and_b32_e32 v97, 0xffff0000, v69
	v_lshlrev_b32_e32 v100, 16, v77
	v_and_b32_e32 v101, 0xffff0000, v77
	v_mul_f32_e32 v94, v31, v93
	v_mul_f32_e32 v95, v35, v93
	v_mul_f32_e32 v98, v31, v97
	v_mul_f32_e32 v99, v35, v97
	v_mul_f32_e32 v102, v31, v101
	v_mul_f32_e32 v103, v35, v101
	v_fmac_f32_e32 v94, v30, v92
	v_fmac_f32_e32 v95, v34, v92
	v_fmac_f32_e32 v98, v30, v96
	v_fmac_f32_e32 v99, v34, v96
	v_fmac_f32_e32 v102, v30, v100
	v_fmac_f32_e32 v103, v34, v100
	v_add_f32_e32 v84, v84, v94
	v_add_f32_e32 v85, v85, v95
	v_add_f32_e32 v86, v86, v98
	v_add_f32_e32 v87, v87, v99
	v_add_f32_e32 v88, v88, v102
	v_add_f32_e32 v89, v89, v103
	v_lshlrev_b32_e32 v92, 16, v62
	v_and_b32_e32 v93, 0xffff0000, v62
	v_lshlrev_b32_e32 v96, 16, v70
	v_and_b32_e32 v97, 0xffff0000, v70
	v_lshlrev_b32_e32 v100, 16, v78
	v_and_b32_e32 v101, 0xffff0000, v78
	v_mul_f32_e32 v94, v37, v93
	v_mul_f32_e32 v95, v41, v93
	v_mul_f32_e32 v98, v37, v97
	v_mul_f32_e32 v99, v41, v97
	v_mul_f32_e32 v102, v37, v101
	v_mul_f32_e32 v103, v41, v101
	v_fmac_f32_e32 v94, v36, v92
	v_fmac_f32_e32 v95, v40, v92
	v_fmac_f32_e32 v98, v36, v96
	v_fmac_f32_e32 v99, v40, v96
	v_fmac_f32_e32 v102, v36, v100
	v_fmac_f32_e32 v103, v40, v100
	v_add_f32_e32 v84, v84, v94
	v_add_f32_e32 v85, v85, v95
	v_add_f32_e32 v86, v86, v98
	v_add_f32_e32 v87, v87, v99
	v_add_f32_e32 v88, v88, v102
	v_add_f32_e32 v89, v89, v103
	v_lshlrev_b32_e32 v92, 16, v63
	v_and_b32_e32 v93, 0xffff0000, v63
	v_lshlrev_b32_e32 v96, 16, v71
	v_and_b32_e32 v97, 0xffff0000, v71
	v_lshlrev_b32_e32 v100, 16, v79
	v_and_b32_e32 v101, 0xffff0000, v79
	v_mul_f32_e32 v94, v39, v93
	v_mul_f32_e32 v95, v43, v93
	v_mul_f32_e32 v98, v39, v97
	v_mul_f32_e32 v99, v43, v97
	v_mul_f32_e32 v102, v39, v101
	v_mul_f32_e32 v103, v43, v101
	v_fmac_f32_e32 v94, v38, v92
	v_fmac_f32_e32 v95, v42, v92
	v_fmac_f32_e32 v98, v38, v96
	v_fmac_f32_e32 v99, v42, v96
	v_fmac_f32_e32 v102, v38, v100
	v_fmac_f32_e32 v103, v42, v100
	v_add_f32_e32 v84, v84, v94
	v_add_f32_e32 v85, v85, v95
	v_add_f32_e32 v86, v86, v98
	v_add_f32_e32 v87, v87, v99
	v_add_f32_e32 v88, v88, v102
	v_add_f32_e32 v89, v89, v103
	v_lshlrev_b32_e32 v92, 16, v64
	v_and_b32_e32 v93, 0xffff0000, v64
	v_lshlrev_b32_e32 v96, 16, v72
	v_and_b32_e32 v97, 0xffff0000, v72
	v_lshlrev_b32_e32 v100, 16, v80
	v_and_b32_e32 v101, 0xffff0000, v80
	v_mul_f32_e32 v94, v45, v93
	v_mul_f32_e32 v95, v49, v93
	v_mul_f32_e32 v98, v45, v97
	v_mul_f32_e32 v99, v49, v97
	v_mul_f32_e32 v102, v45, v101
	v_mul_f32_e32 v103, v49, v101
	v_fmac_f32_e32 v94, v44, v92
	v_fmac_f32_e32 v95, v48, v92
	v_fmac_f32_e32 v98, v44, v96
	v_fmac_f32_e32 v99, v48, v96
	v_fmac_f32_e32 v102, v44, v100
	v_fmac_f32_e32 v103, v48, v100
	v_add_f32_e32 v84, v84, v94
	v_add_f32_e32 v85, v85, v95
	v_add_f32_e32 v86, v86, v98
	v_add_f32_e32 v87, v87, v99
	v_add_f32_e32 v88, v88, v102
	v_add_f32_e32 v89, v89, v103
	v_lshlrev_b32_e32 v92, 16, v65
	v_and_b32_e32 v93, 0xffff0000, v65
	v_lshlrev_b32_e32 v96, 16, v73
	v_and_b32_e32 v97, 0xffff0000, v73
	v_lshlrev_b32_e32 v100, 16, v81
	v_and_b32_e32 v101, 0xffff0000, v81
	v_mul_f32_e32 v94, v47, v93
	v_mul_f32_e32 v95, v51, v93
	v_mul_f32_e32 v98, v47, v97
	v_mul_f32_e32 v99, v51, v97
	v_mul_f32_e32 v102, v47, v101
	v_mul_f32_e32 v103, v51, v101
	v_fmac_f32_e32 v94, v46, v92
	v_fmac_f32_e32 v95, v50, v92
	v_fmac_f32_e32 v98, v46, v96
	v_fmac_f32_e32 v99, v50, v96
	v_fmac_f32_e32 v102, v46, v100
	v_fmac_f32_e32 v103, v50, v100
	v_add_f32_e32 v84, v84, v94
	v_add_f32_e32 v85, v85, v95
	v_add_f32_e32 v86, v86, v98
	v_add_f32_e32 v87, v87, v99
	v_add_f32_e32 v88, v88, v102
	v_add_f32_e32 v89, v89, v103
	v_lshlrev_b32_e32 v92, 16, v66
	v_and_b32_e32 v93, 0xffff0000, v66
	v_lshlrev_b32_e32 v96, 16, v74
	v_and_b32_e32 v97, 0xffff0000, v74
	v_lshlrev_b32_e32 v100, 16, v82
	v_and_b32_e32 v101, 0xffff0000, v82
	v_mul_f32_e32 v94, v53, v93
	v_mul_f32_e32 v95, v57, v93
	v_mul_f32_e32 v98, v53, v97
	v_mul_f32_e32 v99, v57, v97
	v_mul_f32_e32 v102, v53, v101
	v_mul_f32_e32 v103, v57, v101
	v_fmac_f32_e32 v94, v52, v92
	v_fmac_f32_e32 v95, v56, v92
	v_fmac_f32_e32 v98, v52, v96
	v_fmac_f32_e32 v99, v56, v96
	v_fmac_f32_e32 v102, v52, v100
	v_fmac_f32_e32 v103, v56, v100
	v_add_f32_e32 v84, v84, v94
	v_add_f32_e32 v85, v85, v95
	v_add_f32_e32 v86, v86, v98
	v_add_f32_e32 v87, v87, v99
	v_add_f32_e32 v88, v88, v102
	v_add_f32_e32 v89, v89, v103
	v_lshlrev_b32_e32 v92, 16, v67
	v_and_b32_e32 v93, 0xffff0000, v67
	v_lshlrev_b32_e32 v96, 16, v75
	v_and_b32_e32 v97, 0xffff0000, v75
	v_lshlrev_b32_e32 v100, 16, v83
	v_and_b32_e32 v101, 0xffff0000, v83
	v_mul_f32_e32 v94, v55, v93
	v_mul_f32_e32 v95, v59, v93
	v_mul_f32_e32 v98, v55, v97
	v_mul_f32_e32 v99, v59, v97
	v_mul_f32_e32 v102, v55, v101
	v_mul_f32_e32 v103, v59, v101
	v_fmac_f32_e32 v94, v54, v92
	v_fmac_f32_e32 v95, v58, v92
	v_fmac_f32_e32 v98, v54, v96
	v_fmac_f32_e32 v99, v58, v96
	v_fmac_f32_e32 v102, v54, v100
	v_fmac_f32_e32 v103, v58, v100
	v_add_f32_e32 v84, v84, v94
	v_add_f32_e32 v85, v85, v95
	v_add_f32_e32 v86, v86, v98
	v_add_f32_e32 v87, v87, v99
	v_add_f32_e32 v88, v88, v102
	v_add_f32_e32 v89, v89, v103
	s_nop 1
	v_add_f32_dpp v84, v84, v84 quad_perm:[1,0,3,2] row_mask:0xf bank_mask:0xf
	v_add_f32_dpp v85, v85, v85 quad_perm:[1,0,3,2] row_mask:0xf bank_mask:0xf
	v_add_f32_dpp v86, v86, v86 quad_perm:[1,0,3,2] row_mask:0xf bank_mask:0xf
	v_add_f32_dpp v87, v87, v87 quad_perm:[1,0,3,2] row_mask:0xf bank_mask:0xf
	v_add_f32_dpp v88, v88, v88 quad_perm:[1,0,3,2] row_mask:0xf bank_mask:0xf
	v_add_f32_dpp v89, v89, v89 quad_perm:[1,0,3,2] row_mask:0xf bank_mask:0xf
	v_add_f32_dpp v84, v84, v84 quad_perm:[2,3,0,1] row_mask:0xf bank_mask:0xf
	v_add_f32_dpp v85, v85, v85 quad_perm:[2,3,0,1] row_mask:0xf bank_mask:0xf
	v_add_f32_dpp v86, v86, v86 quad_perm:[2,3,0,1] row_mask:0xf bank_mask:0xf
	v_add_f32_dpp v87, v87, v87 quad_perm:[2,3,0,1] row_mask:0xf bank_mask:0xf
	v_add_f32_dpp v88, v88, v88 quad_perm:[2,3,0,1] row_mask:0xf bank_mask:0xf
	v_add_f32_dpp v89, v89, v89 quad_perm:[2,3,0,1] row_mask:0xf bank_mask:0xf
	v_add_f32_dpp v84, v84, v84 row_half_mirror row_mask:0xf bank_mask:0xf
	v_add_f32_dpp v85, v85, v85 row_half_mirror row_mask:0xf bank_mask:0xf
	v_add_f32_dpp v86, v86, v86 row_half_mirror row_mask:0xf bank_mask:0xf
	v_add_f32_dpp v87, v87, v87 row_half_mirror row_mask:0xf bank_mask:0xf
	v_add_f32_dpp v88, v88, v88 row_half_mirror row_mask:0xf bank_mask:0xf
	v_add_f32_dpp v89, v89, v89 row_half_mirror row_mask:0xf bank_mask:0xf
	v_add_f32_dpp v84, v84, v84 row_mirror row_mask:0xf bank_mask:0xf
	v_add_f32_dpp v85, v85, v85 row_mirror row_mask:0xf bank_mask:0xf
	v_add_f32_dpp v86, v86, v86 row_mirror row_mask:0xf bank_mask:0xf
	v_add_f32_dpp v87, v87, v87 row_mirror row_mask:0xf bank_mask:0xf
	v_add_f32_dpp v88, v88, v88 row_mirror row_mask:0xf bank_mask:0xf
	v_add_f32_dpp v89, v89, v89 row_mirror row_mask:0xf bank_mask:0xf
	v_add_f32_dpp v84, v84, v84 row_bcast:15 row_mask:0xa bank_mask:0xf
	v_add_f32_dpp v85, v85, v85 row_bcast:15 row_mask:0xa bank_mask:0xf
	v_add_f32_dpp v86, v86, v86 row_bcast:15 row_mask:0xa bank_mask:0xf
	v_add_f32_dpp v87, v87, v87 row_bcast:15 row_mask:0xa bank_mask:0xf
	v_add_f32_dpp v88, v88, v88 row_bcast:15 row_mask:0xa bank_mask:0xf
	v_add_f32_dpp v89, v89, v89 row_bcast:15 row_mask:0xa bank_mask:0xf
	v_add_f32_dpp v84, v84, v84 row_bcast:31 row_mask:0xc bank_mask:0xf
	v_add_f32_dpp v85, v85, v85 row_bcast:31 row_mask:0xc bank_mask:0xf
	v_add_f32_dpp v86, v86, v86 row_bcast:31 row_mask:0xc bank_mask:0xf
	v_add_f32_dpp v87, v87, v87 row_bcast:31 row_mask:0xc bank_mask:0xf
	v_add_f32_dpp v88, v88, v88 row_bcast:31 row_mask:0xc bank_mask:0xf
	v_add_f32_dpp v89, v89, v89 row_bcast:31 row_mask:0xc bank_mask:0xf
	v_cmp_eq_u32_e32 vcc, 63, v242
	s_lshl_b32 s14, s0, 2
	s_add_u32 s14, s14, 0x2db000
	s_add_u32 s14, s88, s14
	s_addc_u32 s15, s89, 0
	s_lshl_b32 s3, s1, 2
	s_and_saveexec_b64 s[4:5], vcc
	global_store_dword v3, v84, s[14:15]
	s_add_u32 s12, s14, 0x5800
	s_addc_u32 s13, s15, 0
	global_store_dword v3, v85, s[12:13]
	s_add_i32 s0, s0, s1
	s_add_u32 s14, s14, s3
	s_addc_u32 s15, s15, 0
	s_cmpk_lt_i32 s0, 0x1600
	s_cbranch_scc0 .Lcv1_skip1
	global_store_dword v3, v86, s[14:15]
	s_add_u32 s12, s14, 0x5800
	s_addc_u32 s13, s15, 0
	global_store_dword v3, v87, s[12:13]
	s_add_i32 s0, s0, s1
	s_add_u32 s14, s14, s3
	s_addc_u32 s15, s15, 0
	s_cmpk_lt_i32 s0, 0x1600
	s_cbranch_scc0 .Lcv1_skip2
	global_store_dword v3, v88, s[14:15]
	s_add_u32 s12, s14, 0x5800
	s_addc_u32 s13, s15, 0
	global_store_dword v3, v89, s[12:13]
	s_or_b64 exec, exec, s[4:5]
	s_add_i32 s0, s0, s1
	s_cmpk_lt_i32 s0, 0x1600
	s_cbranch_scc1 .Lcv1_loop
	s_branch .LBB0_1116
